# GQA/SWA in-proj first-tile silu-gate epilogue stores write-back (second tile stays write-through), on top of the second-tile write-through q/k/v version
# speedup vs baseline: 1.0020x; 1.0020x over previous
.LBB0_972:
	s_and_b64 vcc, exec, s[4:5]
	s_cbranch_vccz .LBB0_974
	s_cmp_lg_u32 s39, 3
	s_cbranch_scc1 .Lgate_wt
	s_cmp_lg_u32 s62, 0
	s_cbranch_scc1 .Lgate_wt
	s_and_b64 s[4:5], s[22:23], exec
	s_mov_b64 s[4:5], s[0:1]
	s_cselect_b32 s6, -3, -6
	s_load_dwordx2 s[4:5], s[4:5], 0xd0
	s_add_i32 s6, s6, s74
	s_lshl_b32 s6, s6, 8
	s_ashr_i32 s7, s6, 31
	s_lshl_b64 s[6:7], s[6:7], 1
	s_waitcnt lgkmcnt(0)
	s_add_u32 s4, s4, s6
	v_lshlrev_b32_e32 v130, 3, v191
	s_addc_u32 s5, s5, s7
	v_ashrrev_i32_e32 v131, 31, v130
	v_readlane_b32 s6, v254, 45
	v_lshl_add_u64 v[130:131], v[130:131], 1, s[4:5]
	s_mov_b64 s[4:5], 0x6000000
	v_or_b32_e32 v112, s6, v189
	v_lshl_add_u64 v[130:131], v[130:131], 0, s[4:5]
	v_readlane_b32 s4, v254, 36
	s_cmp_eq_u32 s39, 3
	v_readlane_b32 s5, v254, 37
	v_lshl_add_u32 v132, s4, 8, v112
	v_ashrrev_i32_e32 v133, 31, v132
	v_mul_f32_e32 v112, 0xbfb8aa3b, v126
	v_lshlrev_b64 v[134:135], 11, v[132:133]
	v_exp_f32_e32 v112, v112
	v_mul_f32_e32 v133, 0xbfb8aa3b, v127
	v_exp_f32_e32 v133, v133
	v_lshl_add_u64 v[138:139], v[130:131], 0, v[134:135]
	v_add_f32_e32 v112, 1.0, v112
	v_rcp_f32_e32 v134, v112
	v_add_f32_e32 v112, 1.0, v133
	v_mul_f32_e32 v133, 0xbfb8aa3b, v128
	v_exp_f32_e32 v133, v133
	v_mul_f32_e32 v135, 0xbfb8aa3b, v129
	v_exp_f32_e32 v137, v135
	v_rcp_f32_e32 v135, v112
	v_add_f32_e32 v112, 1.0, v133
	v_mul_f32_e32 v133, 0xbfb8aa3b, v122
	v_rcp_f32_e32 v136, v112
	v_add_f32_e32 v112, 1.0, v137
	v_exp_f32_e32 v133, v133
	v_mul_f32_e32 v137, 0xbfb8aa3b, v123
	v_exp_f32_e32 v141, v137
	v_rcp_f32_e32 v137, v112
	v_add_f32_e32 v112, 1.0, v133
	v_mul_f32_e32 v133, 0xbfb8aa3b, v124
	v_rcp_f32_e32 v140, v112
	v_add_f32_e32 v112, 1.0, v141
	v_exp_f32_e32 v133, v133
	v_mul_f32_e32 v141, 0xbfb8aa3b, v125
	v_exp_f32_e32 v143, v141
	v_rcp_f32_e32 v141, v112
	v_add_f32_e32 v112, 1.0, v133
	v_rcp_f32_e32 v142, v112
	v_add_f32_e32 v112, 1.0, v143
	v_rcp_f32_e32 v143, v112
	v_mul_f32_e32 v112, 0xbfb8aa3b, v118
	v_exp_f32_e32 v112, v112
	v_mul_f32_e32 v133, 0xbfb8aa3b, v119
	v_readlane_b32 s4, v255, 29
	v_exp_f32_e32 v133, v133
	s_cselect_b32 s4, s19, s4
	v_readlane_b32 s5, v255, 28
	v_readlane_b32 s6, v255, 30
	v_pk_mul_f32 v[134:135], v[126:127], v[134:135]
	v_pk_mul_f32 v[136:137], v[128:129], v[136:137]
	v_pk_mul_f32 v[140:141], v[122:123], v[140:141]
	v_pk_mul_f32 v[142:143], v[124:125], v[142:143]
	s_cselect_b32 s6, s5, s6
	s_lshl_b32 s4, s4, 1
	s_mov_b32 s5, s15
	v_cvt_pk_bf16_f32 v134, v134, v135
	v_cvt_pk_bf16_f32 v135, v136, v137
	v_cvt_pk_bf16_f32 v136, v140, v141
	v_cvt_pk_bf16_f32 v137, v142, v143
	v_lshl_add_u64 v[140:141], v[138:139], 0, s[4:5]
	v_add_f32_e32 v112, 1.0, v112
	global_store_dwordx4 v[140:141], v[134:137], off
	s_lshl_b32 s6, s6, 1
	s_mov_b32 s7, s15
	v_rcp_f32_e32 v134, v112
	v_add_f32_e32 v112, 1.0, v133
	v_mul_f32_e32 v133, 0xbfb8aa3b, v120
	v_exp_f32_e32 v133, v133
	v_mul_f32_e32 v135, 0xbfb8aa3b, v121
	v_exp_f32_e32 v137, v135
	v_rcp_f32_e32 v135, v112
	v_add_f32_e32 v112, 1.0, v133
	v_mul_f32_e32 v133, 0xbfb8aa3b, v114
	v_rcp_f32_e32 v136, v112
	v_add_f32_e32 v112, 1.0, v137
	v_exp_f32_e32 v133, v133
	v_mul_f32_e32 v137, 0xbfb8aa3b, v115
	v_exp_f32_e32 v141, v137
	v_rcp_f32_e32 v137, v112
	v_add_f32_e32 v112, 1.0, v133
	v_mul_f32_e32 v133, 0xbfb8aa3b, v116
	v_rcp_f32_e32 v140, v112
	v_add_f32_e32 v112, 1.0, v141
	v_exp_f32_e32 v133, v133
	v_mul_f32_e32 v141, 0xbfb8aa3b, v117
	v_exp_f32_e32 v143, v141
	v_rcp_f32_e32 v141, v112
	v_add_f32_e32 v112, 1.0, v133
	v_rcp_f32_e32 v142, v112
	v_add_f32_e32 v112, 1.0, v143
	v_rcp_f32_e32 v143, v112
	v_mul_f32_e32 v112, 0xbfb8aa3b, v108
	v_pk_mul_f32 v[134:135], v[118:119], v[134:135]
	v_pk_mul_f32 v[136:137], v[120:121], v[136:137]
	v_pk_mul_f32 v[140:141], v[114:115], v[140:141]
	v_pk_mul_f32 v[142:143], v[116:117], v[142:143]
	v_exp_f32_e32 v112, v112
	v_mul_f32_e32 v133, 0xbfb8aa3b, v109
	v_cvt_pk_bf16_f32 v134, v134, v135
	v_cvt_pk_bf16_f32 v135, v136, v137
	v_cvt_pk_bf16_f32 v136, v140, v141
	v_cvt_pk_bf16_f32 v137, v142, v143
	v_lshl_add_u64 v[138:139], v[138:139], 0, s[6:7]
	v_exp_f32_e32 v133, v133
	global_store_dwordx4 v[138:139], v[134:137], off
	v_add_f32_e32 v112, 1.0, v112
	s_nop 0
	v_or_b32_e32 v134, 16, v132
	v_ashrrev_i32_e32 v135, 31, v134
	v_lshlrev_b64 v[134:135], 11, v[134:135]
	v_lshl_add_u64 v[138:139], v[130:131], 0, v[134:135]
	v_rcp_f32_e32 v134, v112
	v_add_f32_e32 v112, 1.0, v133
	v_mul_f32_e32 v133, 0xbfb8aa3b, v110
	v_exp_f32_e32 v133, v133
	v_mul_f32_e32 v135, 0xbfb8aa3b, v111
	v_exp_f32_e32 v137, v135
	v_rcp_f32_e32 v135, v112
	v_add_f32_e32 v112, 1.0, v133
	v_mul_f32_e32 v133, 0xbfb8aa3b, v104
	v_rcp_f32_e32 v136, v112
	v_add_f32_e32 v112, 1.0, v137
	v_exp_f32_e32 v133, v133
	v_mul_f32_e32 v137, 0xbfb8aa3b, v105
	v_exp_f32_e32 v141, v137
	v_rcp_f32_e32 v137, v112
	v_add_f32_e32 v112, 1.0, v133
	v_mul_f32_e32 v133, 0xbfb8aa3b, v106
	v_rcp_f32_e32 v140, v112
	v_add_f32_e32 v112, 1.0, v141
	v_exp_f32_e32 v133, v133
	v_mul_f32_e32 v141, 0xbfb8aa3b, v107
	v_exp_f32_e32 v143, v141
	v_rcp_f32_e32 v141, v112
	v_add_f32_e32 v112, 1.0, v133
	v_rcp_f32_e32 v142, v112
	v_add_f32_e32 v112, 1.0, v143
	v_rcp_f32_e32 v143, v112
	v_mul_f32_e32 v112, 0xbfb8aa3b, v100
	v_exp_f32_e32 v112, v112
	v_mul_f32_e32 v133, 0xbfb8aa3b, v101
	v_exp_f32_e32 v133, v133
	v_pk_mul_f32 v[134:135], v[108:109], v[134:135]
	v_pk_mul_f32 v[136:137], v[110:111], v[136:137]
	v_pk_mul_f32 v[140:141], v[104:105], v[140:141]
	v_pk_mul_f32 v[142:143], v[106:107], v[142:143]
	v_cvt_pk_bf16_f32 v134, v134, v135
	v_cvt_pk_bf16_f32 v135, v136, v137
	v_cvt_pk_bf16_f32 v136, v140, v141
	v_cvt_pk_bf16_f32 v137, v142, v143
	v_lshl_add_u64 v[140:141], v[138:139], 0, s[4:5]
	v_add_f32_e32 v112, 1.0, v112
	global_store_dwordx4 v[140:141], v[134:137], off
	v_lshl_add_u64 v[138:139], v[138:139], 0, s[6:7]
	s_nop 0
	v_rcp_f32_e32 v134, v112
	v_add_f32_e32 v112, 1.0, v133
	v_mul_f32_e32 v133, 0xbfb8aa3b, v102
	v_exp_f32_e32 v133, v133
	v_mul_f32_e32 v135, 0xbfb8aa3b, v103
	v_exp_f32_e32 v137, v135
	v_rcp_f32_e32 v135, v112
	v_add_f32_e32 v112, 1.0, v133
	v_mul_f32_e32 v133, 0xbfb8aa3b, v96
	v_rcp_f32_e32 v136, v112
	v_add_f32_e32 v112, 1.0, v137
	v_exp_f32_e32 v133, v133
	v_mul_f32_e32 v137, 0xbfb8aa3b, v97
	v_exp_f32_e32 v141, v137
	v_rcp_f32_e32 v137, v112
	v_add_f32_e32 v112, 1.0, v133
	v_mul_f32_e32 v133, 0xbfb8aa3b, v98
	v_rcp_f32_e32 v140, v112
	v_add_f32_e32 v112, 1.0, v141
	v_exp_f32_e32 v133, v133
	v_mul_f32_e32 v141, 0xbfb8aa3b, v99
	v_exp_f32_e32 v143, v141
	v_rcp_f32_e32 v141, v112
	v_add_f32_e32 v112, 1.0, v133
	v_rcp_f32_e32 v142, v112
	v_add_f32_e32 v112, 1.0, v143
	v_rcp_f32_e32 v143, v112
	v_mul_f32_e32 v112, 0xbfb8aa3b, v92
	v_pk_mul_f32 v[134:135], v[100:101], v[134:135]
	v_pk_mul_f32 v[136:137], v[102:103], v[136:137]
	v_pk_mul_f32 v[140:141], v[96:97], v[140:141]
	v_pk_mul_f32 v[142:143], v[98:99], v[142:143]
	v_exp_f32_e32 v112, v112
	v_mul_f32_e32 v133, 0xbfb8aa3b, v93
	v_cvt_pk_bf16_f32 v134, v134, v135
	v_cvt_pk_bf16_f32 v135, v136, v137
	v_cvt_pk_bf16_f32 v136, v140, v141
	v_cvt_pk_bf16_f32 v137, v142, v143
	v_exp_f32_e32 v133, v133
	global_store_dwordx4 v[138:139], v[134:137], off
	v_add_f32_e32 v112, 1.0, v112
	s_nop 0
	v_or_b32_e32 v134, 32, v132
	v_ashrrev_i32_e32 v135, 31, v134
	v_lshlrev_b64 v[134:135], 11, v[134:135]
	v_lshl_add_u64 v[138:139], v[130:131], 0, v[134:135]
	v_rcp_f32_e32 v134, v112
	v_add_f32_e32 v112, 1.0, v133
	v_mul_f32_e32 v133, 0xbfb8aa3b, v94
	v_exp_f32_e32 v133, v133
	v_mul_f32_e32 v135, 0xbfb8aa3b, v95
	v_exp_f32_e32 v137, v135
	v_rcp_f32_e32 v135, v112
	v_add_f32_e32 v112, 1.0, v133
	v_mul_f32_e32 v133, 0xbfb8aa3b, v88
	v_rcp_f32_e32 v136, v112
	v_add_f32_e32 v112, 1.0, v137
	v_exp_f32_e32 v133, v133
	v_mul_f32_e32 v137, 0xbfb8aa3b, v89
	v_exp_f32_e32 v141, v137
	v_rcp_f32_e32 v137, v112
	v_add_f32_e32 v112, 1.0, v133
	v_mul_f32_e32 v133, 0xbfb8aa3b, v90
	v_rcp_f32_e32 v140, v112
	v_add_f32_e32 v112, 1.0, v141
	v_exp_f32_e32 v133, v133
	v_mul_f32_e32 v141, 0xbfb8aa3b, v91
	v_exp_f32_e32 v143, v141
	v_rcp_f32_e32 v141, v112
	v_add_f32_e32 v112, 1.0, v133
	v_rcp_f32_e32 v142, v112
	v_add_f32_e32 v112, 1.0, v143
	v_rcp_f32_e32 v143, v112
	v_mul_f32_e32 v112, 0xbfb8aa3b, v84
	v_exp_f32_e32 v112, v112
	v_mul_f32_e32 v133, 0xbfb8aa3b, v85
	v_exp_f32_e32 v133, v133
	v_pk_mul_f32 v[134:135], v[92:93], v[134:135]
	v_pk_mul_f32 v[136:137], v[94:95], v[136:137]
	v_pk_mul_f32 v[140:141], v[88:89], v[140:141]
	v_pk_mul_f32 v[142:143], v[90:91], v[142:143]
	v_cvt_pk_bf16_f32 v134, v134, v135
	v_cvt_pk_bf16_f32 v135, v136, v137
	v_cvt_pk_bf16_f32 v136, v140, v141
	v_cvt_pk_bf16_f32 v137, v142, v143
	v_lshl_add_u64 v[140:141], v[138:139], 0, s[4:5]
	v_add_f32_e32 v112, 1.0, v112
	global_store_dwordx4 v[140:141], v[134:137], off
	v_lshl_add_u64 v[138:139], v[138:139], 0, s[6:7]
	s_nop 0
	v_rcp_f32_e32 v134, v112
	v_add_f32_e32 v112, 1.0, v133
	v_mul_f32_e32 v133, 0xbfb8aa3b, v86
	v_exp_f32_e32 v133, v133
	v_mul_f32_e32 v135, 0xbfb8aa3b, v87
	v_exp_f32_e32 v137, v135
	v_rcp_f32_e32 v135, v112
	v_add_f32_e32 v112, 1.0, v133
	v_mul_f32_e32 v133, 0xbfb8aa3b, v80
	v_rcp_f32_e32 v136, v112
	v_add_f32_e32 v112, 1.0, v137
	v_exp_f32_e32 v133, v133
	v_mul_f32_e32 v137, 0xbfb8aa3b, v81
	v_exp_f32_e32 v141, v137
	v_rcp_f32_e32 v137, v112
	v_add_f32_e32 v112, 1.0, v133
	v_mul_f32_e32 v133, 0xbfb8aa3b, v82
	v_rcp_f32_e32 v140, v112
	v_add_f32_e32 v112, 1.0, v141
	v_exp_f32_e32 v133, v133
	v_mul_f32_e32 v141, 0xbfb8aa3b, v83
	v_exp_f32_e32 v143, v141
	v_rcp_f32_e32 v141, v112
	v_add_f32_e32 v112, 1.0, v133
	v_rcp_f32_e32 v142, v112
	v_add_f32_e32 v112, 1.0, v143
	v_rcp_f32_e32 v143, v112
	v_mul_f32_e32 v112, 0xbfb8aa3b, v76
	v_pk_mul_f32 v[134:135], v[84:85], v[134:135]
	v_pk_mul_f32 v[136:137], v[86:87], v[136:137]
	v_pk_mul_f32 v[140:141], v[80:81], v[140:141]
	v_pk_mul_f32 v[142:143], v[82:83], v[142:143]
	v_exp_f32_e32 v112, v112
	v_mul_f32_e32 v133, 0xbfb8aa3b, v77
	v_cvt_pk_bf16_f32 v134, v134, v135
	v_cvt_pk_bf16_f32 v135, v136, v137
	v_cvt_pk_bf16_f32 v136, v140, v141
	v_cvt_pk_bf16_f32 v137, v142, v143
	v_exp_f32_e32 v133, v133
	global_store_dwordx4 v[138:139], v[134:137], off
	v_add_f32_e32 v112, 1.0, v112
	s_nop 0
	v_or_b32_e32 v134, 48, v132
	v_ashrrev_i32_e32 v135, 31, v134
	v_lshlrev_b64 v[134:135], 11, v[134:135]
	v_lshl_add_u64 v[138:139], v[130:131], 0, v[134:135]
	v_rcp_f32_e32 v134, v112
	v_add_f32_e32 v112, 1.0, v133
	v_mul_f32_e32 v133, 0xbfb8aa3b, v78
	v_exp_f32_e32 v133, v133
	v_mul_f32_e32 v135, 0xbfb8aa3b, v79
	v_exp_f32_e32 v137, v135
	v_rcp_f32_e32 v135, v112
	v_add_f32_e32 v112, 1.0, v133
	v_mul_f32_e32 v133, 0xbfb8aa3b, v72
	v_rcp_f32_e32 v136, v112
	v_add_f32_e32 v112, 1.0, v137
	v_exp_f32_e32 v133, v133
	v_mul_f32_e32 v137, 0xbfb8aa3b, v73
	v_exp_f32_e32 v141, v137
	v_rcp_f32_e32 v137, v112
	v_add_f32_e32 v112, 1.0, v133
	v_mul_f32_e32 v133, 0xbfb8aa3b, v74
	v_rcp_f32_e32 v140, v112
	v_add_f32_e32 v112, 1.0, v141
	v_exp_f32_e32 v133, v133
	v_mul_f32_e32 v141, 0xbfb8aa3b, v75
	v_exp_f32_e32 v143, v141
	v_rcp_f32_e32 v141, v112
	v_add_f32_e32 v112, 1.0, v133
	v_rcp_f32_e32 v142, v112
	v_add_f32_e32 v112, 1.0, v143
	v_rcp_f32_e32 v143, v112
	v_mul_f32_e32 v112, 0xbfb8aa3b, v68
	v_exp_f32_e32 v112, v112
	v_mul_f32_e32 v133, 0xbfb8aa3b, v69
	v_exp_f32_e32 v133, v133
	v_pk_mul_f32 v[134:135], v[76:77], v[134:135]
	v_pk_mul_f32 v[136:137], v[78:79], v[136:137]
	v_pk_mul_f32 v[140:141], v[72:73], v[140:141]
	v_pk_mul_f32 v[142:143], v[74:75], v[142:143]
	v_cvt_pk_bf16_f32 v134, v134, v135
	v_cvt_pk_bf16_f32 v135, v136, v137
	v_cvt_pk_bf16_f32 v136, v140, v141
	v_cvt_pk_bf16_f32 v137, v142, v143
	v_lshl_add_u64 v[140:141], v[138:139], 0, s[4:5]
	v_add_f32_e32 v112, 1.0, v112
	global_store_dwordx4 v[140:141], v[134:137], off
	v_lshl_add_u64 v[138:139], v[138:139], 0, s[6:7]
	s_nop 0
	v_rcp_f32_e32 v134, v112
	v_add_f32_e32 v112, 1.0, v133
	v_mul_f32_e32 v133, 0xbfb8aa3b, v70
	v_exp_f32_e32 v133, v133
	v_mul_f32_e32 v135, 0xbfb8aa3b, v71
	v_exp_f32_e32 v137, v135
	v_rcp_f32_e32 v135, v112
	v_add_f32_e32 v112, 1.0, v133
	v_mul_f32_e32 v133, 0xbfb8aa3b, v64
	v_rcp_f32_e32 v136, v112
	v_add_f32_e32 v112, 1.0, v137
	v_exp_f32_e32 v133, v133
	v_mul_f32_e32 v137, 0xbfb8aa3b, v65
	v_exp_f32_e32 v141, v137
	v_rcp_f32_e32 v137, v112
	v_add_f32_e32 v112, 1.0, v133
	v_mul_f32_e32 v133, 0xbfb8aa3b, v66
	v_rcp_f32_e32 v140, v112
	v_add_f32_e32 v112, 1.0, v141
	v_exp_f32_e32 v133, v133
	v_mul_f32_e32 v141, 0xbfb8aa3b, v67
	v_exp_f32_e32 v143, v141
	v_rcp_f32_e32 v141, v112
	v_add_f32_e32 v112, 1.0, v133
	v_rcp_f32_e32 v142, v112
	v_add_f32_e32 v112, 1.0, v143
	v_rcp_f32_e32 v143, v112
	v_mul_f32_e32 v112, 0xbfb8aa3b, v60
	v_pk_mul_f32 v[134:135], v[68:69], v[134:135]
	v_pk_mul_f32 v[136:137], v[70:71], v[136:137]
	v_pk_mul_f32 v[140:141], v[64:65], v[140:141]
	v_pk_mul_f32 v[142:143], v[66:67], v[142:143]
	v_exp_f32_e32 v112, v112
	v_mul_f32_e32 v133, 0xbfb8aa3b, v61
	v_cvt_pk_bf16_f32 v134, v134, v135
	v_cvt_pk_bf16_f32 v135, v136, v137
	v_cvt_pk_bf16_f32 v136, v140, v141
	v_cvt_pk_bf16_f32 v137, v142, v143
	v_exp_f32_e32 v133, v133
	global_store_dwordx4 v[138:139], v[134:137], off
	v_add_f32_e32 v112, 1.0, v112
	s_nop 0
	v_add_u32_e32 v134, 0x80, v132
	v_ashrrev_i32_e32 v135, 31, v134
	v_lshlrev_b64 v[134:135], 11, v[134:135]
	v_lshl_add_u64 v[138:139], v[130:131], 0, v[134:135]
	v_rcp_f32_e32 v134, v112
	v_add_f32_e32 v112, 1.0, v133
	v_mul_f32_e32 v133, 0xbfb8aa3b, v62
	v_exp_f32_e32 v133, v133
	v_mul_f32_e32 v135, 0xbfb8aa3b, v63
	v_exp_f32_e32 v137, v135
	v_rcp_f32_e32 v135, v112
	v_add_f32_e32 v112, 1.0, v133
	v_mul_f32_e32 v133, 0xbfb8aa3b, v56
	v_rcp_f32_e32 v136, v112
	v_add_f32_e32 v112, 1.0, v137
	v_exp_f32_e32 v133, v133
	v_mul_f32_e32 v137, 0xbfb8aa3b, v57
	v_exp_f32_e32 v141, v137
	v_rcp_f32_e32 v137, v112
	v_add_f32_e32 v112, 1.0, v133
	v_mul_f32_e32 v133, 0xbfb8aa3b, v58
	v_rcp_f32_e32 v140, v112
	v_add_f32_e32 v112, 1.0, v141
	v_exp_f32_e32 v133, v133
	v_mul_f32_e32 v141, 0xbfb8aa3b, v59
	v_exp_f32_e32 v143, v141
	v_rcp_f32_e32 v141, v112
	v_add_f32_e32 v112, 1.0, v133
	v_rcp_f32_e32 v142, v112
	v_add_f32_e32 v112, 1.0, v143
	v_rcp_f32_e32 v143, v112
	v_mul_f32_e32 v112, 0xbfb8aa3b, v52
	v_exp_f32_e32 v112, v112
	v_mul_f32_e32 v133, 0xbfb8aa3b, v53
	v_exp_f32_e32 v133, v133
	v_pk_mul_f32 v[134:135], v[60:61], v[134:135]
	v_pk_mul_f32 v[136:137], v[62:63], v[136:137]
	v_pk_mul_f32 v[140:141], v[56:57], v[140:141]
	v_pk_mul_f32 v[142:143], v[58:59], v[142:143]
	v_cvt_pk_bf16_f32 v134, v134, v135
	v_cvt_pk_bf16_f32 v135, v136, v137
	v_cvt_pk_bf16_f32 v136, v140, v141
	v_cvt_pk_bf16_f32 v137, v142, v143
	v_lshl_add_u64 v[140:141], v[138:139], 0, s[4:5]
	v_add_f32_e32 v112, 1.0, v112
	global_store_dwordx4 v[140:141], v[134:137], off
	v_lshl_add_u64 v[138:139], v[138:139], 0, s[6:7]
	s_nop 0
	v_rcp_f32_e32 v134, v112
	v_add_f32_e32 v112, 1.0, v133
	v_mul_f32_e32 v133, 0xbfb8aa3b, v54
	v_exp_f32_e32 v133, v133
	v_mul_f32_e32 v135, 0xbfb8aa3b, v55
	v_exp_f32_e32 v137, v135
	v_rcp_f32_e32 v135, v112
	v_add_f32_e32 v112, 1.0, v133
	v_mul_f32_e32 v133, 0xbfb8aa3b, v48
	v_rcp_f32_e32 v136, v112
	v_add_f32_e32 v112, 1.0, v137
	v_exp_f32_e32 v133, v133
	v_mul_f32_e32 v137, 0xbfb8aa3b, v49
	v_exp_f32_e32 v141, v137
	v_rcp_f32_e32 v137, v112
	v_add_f32_e32 v112, 1.0, v133
	v_mul_f32_e32 v133, 0xbfb8aa3b, v50
	v_rcp_f32_e32 v140, v112
	v_add_f32_e32 v112, 1.0, v141
	v_exp_f32_e32 v133, v133
	v_mul_f32_e32 v141, 0xbfb8aa3b, v51
	v_exp_f32_e32 v143, v141
	v_rcp_f32_e32 v141, v112
	v_add_f32_e32 v112, 1.0, v133
	v_rcp_f32_e32 v142, v112
	v_add_f32_e32 v112, 1.0, v143
	v_rcp_f32_e32 v143, v112
	v_mul_f32_e32 v112, 0xbfb8aa3b, v44
	v_pk_mul_f32 v[134:135], v[52:53], v[134:135]
	v_pk_mul_f32 v[136:137], v[54:55], v[136:137]
	v_pk_mul_f32 v[140:141], v[48:49], v[140:141]
	v_pk_mul_f32 v[142:143], v[50:51], v[142:143]
	v_exp_f32_e32 v112, v112
	v_mul_f32_e32 v133, 0xbfb8aa3b, v45
	v_cvt_pk_bf16_f32 v134, v134, v135
	v_cvt_pk_bf16_f32 v135, v136, v137
	v_cvt_pk_bf16_f32 v136, v140, v141
	v_cvt_pk_bf16_f32 v137, v142, v143
	v_exp_f32_e32 v133, v133
	global_store_dwordx4 v[138:139], v[134:137], off
	v_add_f32_e32 v112, 1.0, v112
	s_nop 0
	v_add_u32_e32 v134, 0x90, v132
	v_ashrrev_i32_e32 v135, 31, v134
	v_lshlrev_b64 v[134:135], 11, v[134:135]
	v_lshl_add_u64 v[138:139], v[130:131], 0, v[134:135]
	v_rcp_f32_e32 v134, v112
	v_add_f32_e32 v112, 1.0, v133
	v_mul_f32_e32 v133, 0xbfb8aa3b, v46
	v_exp_f32_e32 v133, v133
	v_mul_f32_e32 v135, 0xbfb8aa3b, v47
	v_exp_f32_e32 v137, v135
	v_rcp_f32_e32 v135, v112
	v_add_f32_e32 v112, 1.0, v133
	v_mul_f32_e32 v133, 0xbfb8aa3b, v40
	v_rcp_f32_e32 v136, v112
	v_add_f32_e32 v112, 1.0, v137
	v_exp_f32_e32 v133, v133
	v_mul_f32_e32 v137, 0xbfb8aa3b, v41
	v_exp_f32_e32 v141, v137
	v_rcp_f32_e32 v137, v112
	v_add_f32_e32 v112, 1.0, v133
	v_mul_f32_e32 v133, 0xbfb8aa3b, v42
	v_rcp_f32_e32 v140, v112
	v_add_f32_e32 v112, 1.0, v141
	v_exp_f32_e32 v133, v133
	v_mul_f32_e32 v141, 0xbfb8aa3b, v43
	v_exp_f32_e32 v143, v141
	v_rcp_f32_e32 v141, v112
	v_add_f32_e32 v112, 1.0, v133
	v_rcp_f32_e32 v142, v112
	v_add_f32_e32 v112, 1.0, v143
	v_rcp_f32_e32 v143, v112
	v_mul_f32_e32 v112, 0xbfb8aa3b, v36
	v_exp_f32_e32 v112, v112
	v_mul_f32_e32 v133, 0xbfb8aa3b, v37
	v_exp_f32_e32 v133, v133
	v_pk_mul_f32 v[134:135], v[44:45], v[134:135]
	v_pk_mul_f32 v[136:137], v[46:47], v[136:137]
	v_pk_mul_f32 v[140:141], v[40:41], v[140:141]
	v_pk_mul_f32 v[142:143], v[42:43], v[142:143]
	v_cvt_pk_bf16_f32 v134, v134, v135
	v_cvt_pk_bf16_f32 v135, v136, v137
	v_cvt_pk_bf16_f32 v136, v140, v141
	v_cvt_pk_bf16_f32 v137, v142, v143
	v_lshl_add_u64 v[140:141], v[138:139], 0, s[4:5]
	v_add_f32_e32 v112, 1.0, v112
	global_store_dwordx4 v[140:141], v[134:137], off
	v_lshl_add_u64 v[138:139], v[138:139], 0, s[6:7]
	s_nop 0
	v_rcp_f32_e32 v134, v112
	v_add_f32_e32 v112, 1.0, v133
	v_mul_f32_e32 v133, 0xbfb8aa3b, v38
	v_exp_f32_e32 v133, v133
	v_mul_f32_e32 v135, 0xbfb8aa3b, v39
	v_exp_f32_e32 v137, v135
	v_rcp_f32_e32 v135, v112
	v_add_f32_e32 v112, 1.0, v133
	v_mul_f32_e32 v133, 0xbfb8aa3b, v32
	v_rcp_f32_e32 v136, v112
	v_add_f32_e32 v112, 1.0, v137
	v_exp_f32_e32 v133, v133
	v_mul_f32_e32 v137, 0xbfb8aa3b, v33
	v_exp_f32_e32 v141, v137
	v_rcp_f32_e32 v137, v112
	v_add_f32_e32 v112, 1.0, v133
	v_mul_f32_e32 v133, 0xbfb8aa3b, v34
	v_rcp_f32_e32 v140, v112
	v_add_f32_e32 v112, 1.0, v141
	v_exp_f32_e32 v133, v133
	v_mul_f32_e32 v141, 0xbfb8aa3b, v35
	v_exp_f32_e32 v143, v141
	v_rcp_f32_e32 v141, v112
	v_add_f32_e32 v112, 1.0, v133
	v_rcp_f32_e32 v142, v112
	v_add_f32_e32 v112, 1.0, v143
	v_rcp_f32_e32 v143, v112
	v_mul_f32_e32 v112, 0xbfb8aa3b, v28
	v_pk_mul_f32 v[134:135], v[36:37], v[134:135]
	v_pk_mul_f32 v[136:137], v[38:39], v[136:137]
	v_pk_mul_f32 v[140:141], v[32:33], v[140:141]
	v_pk_mul_f32 v[142:143], v[34:35], v[142:143]
	v_exp_f32_e32 v112, v112
	v_mul_f32_e32 v133, 0xbfb8aa3b, v29
	v_cvt_pk_bf16_f32 v134, v134, v135
	v_cvt_pk_bf16_f32 v135, v136, v137
	v_cvt_pk_bf16_f32 v136, v140, v141
	v_cvt_pk_bf16_f32 v137, v142, v143
	v_exp_f32_e32 v133, v133
	global_store_dwordx4 v[138:139], v[134:137], off
	v_add_f32_e32 v112, 1.0, v112
	s_nop 0
	v_add_u32_e32 v134, 0xa0, v132
	v_ashrrev_i32_e32 v135, 31, v134
	v_lshlrev_b64 v[134:135], 11, v[134:135]
	v_lshl_add_u64 v[138:139], v[130:131], 0, v[134:135]
	v_rcp_f32_e32 v134, v112
	v_add_f32_e32 v112, 1.0, v133
	v_mul_f32_e32 v133, 0xbfb8aa3b, v30
	v_exp_f32_e32 v133, v133
	v_mul_f32_e32 v135, 0xbfb8aa3b, v31
	v_exp_f32_e32 v137, v135
	v_rcp_f32_e32 v135, v112
	v_add_f32_e32 v112, 1.0, v133
	v_mul_f32_e32 v133, 0xbfb8aa3b, v24
	v_rcp_f32_e32 v136, v112
	v_add_f32_e32 v112, 1.0, v137
	v_exp_f32_e32 v133, v133
	v_mul_f32_e32 v137, 0xbfb8aa3b, v25
	v_exp_f32_e32 v141, v137
	v_rcp_f32_e32 v137, v112
	v_add_f32_e32 v112, 1.0, v133
	v_mul_f32_e32 v133, 0xbfb8aa3b, v26
	v_rcp_f32_e32 v140, v112
	v_add_f32_e32 v112, 1.0, v141
	v_exp_f32_e32 v133, v133
	v_mul_f32_e32 v141, 0xbfb8aa3b, v27
	v_exp_f32_e32 v143, v141
	v_rcp_f32_e32 v141, v112
	v_add_f32_e32 v112, 1.0, v133
	v_rcp_f32_e32 v142, v112
	v_add_f32_e32 v112, 1.0, v143
	v_rcp_f32_e32 v143, v112
	v_mul_f32_e32 v112, 0xbfb8aa3b, v20
	v_exp_f32_e32 v112, v112
	v_mul_f32_e32 v133, 0xbfb8aa3b, v21
	v_exp_f32_e32 v133, v133
	v_pk_mul_f32 v[134:135], v[28:29], v[134:135]
	v_pk_mul_f32 v[136:137], v[30:31], v[136:137]
	v_pk_mul_f32 v[140:141], v[24:25], v[140:141]
	v_pk_mul_f32 v[142:143], v[26:27], v[142:143]
	v_cvt_pk_bf16_f32 v134, v134, v135
	v_cvt_pk_bf16_f32 v135, v136, v137
	v_cvt_pk_bf16_f32 v136, v140, v141
	v_cvt_pk_bf16_f32 v137, v142, v143
	v_lshl_add_u64 v[140:141], v[138:139], 0, s[4:5]
	v_add_f32_e32 v112, 1.0, v112
	global_store_dwordx4 v[140:141], v[134:137], off
	v_add_u32_e32 v132, 0xb0, v132
	v_lshl_add_u64 v[138:139], v[138:139], 0, s[6:7]
	v_rcp_f32_e32 v134, v112
	v_add_f32_e32 v112, 1.0, v133
	v_mul_f32_e32 v133, 0xbfb8aa3b, v22
	v_exp_f32_e32 v133, v133
	v_mul_f32_e32 v135, 0xbfb8aa3b, v23
	v_exp_f32_e32 v137, v135
	v_rcp_f32_e32 v135, v112
	v_add_f32_e32 v112, 1.0, v133
	v_mul_f32_e32 v133, 0xbfb8aa3b, v16
	v_rcp_f32_e32 v136, v112
	v_add_f32_e32 v112, 1.0, v137
	v_exp_f32_e32 v133, v133
	v_mul_f32_e32 v137, 0xbfb8aa3b, v17
	v_exp_f32_e32 v141, v137
	v_rcp_f32_e32 v137, v112
	v_add_f32_e32 v112, 1.0, v133
	v_mul_f32_e32 v133, 0xbfb8aa3b, v18
	v_rcp_f32_e32 v140, v112
	v_add_f32_e32 v112, 1.0, v141
	v_exp_f32_e32 v133, v133
	v_mul_f32_e32 v141, 0xbfb8aa3b, v19
	v_exp_f32_e32 v143, v141
	v_rcp_f32_e32 v141, v112
	v_add_f32_e32 v112, 1.0, v133
	v_rcp_f32_e32 v142, v112
	v_add_f32_e32 v112, 1.0, v143
	v_rcp_f32_e32 v143, v112
	v_pk_mul_f32 v[134:135], v[20:21], v[134:135]
	v_pk_mul_f32 v[136:137], v[22:23], v[136:137]
	v_pk_mul_f32 v[140:141], v[16:17], v[140:141]
	v_pk_mul_f32 v[142:143], v[18:19], v[142:143]
	v_cvt_pk_bf16_f32 v134, v134, v135
	v_cvt_pk_bf16_f32 v135, v136, v137
	v_cvt_pk_bf16_f32 v136, v140, v141
	v_cvt_pk_bf16_f32 v137, v142, v143
	v_ashrrev_i32_e32 v133, 31, v132
	v_mul_f32_e32 v112, 0xbfb8aa3b, v12
	global_store_dwordx4 v[138:139], v[134:137], off
	v_lshlrev_b64 v[132:133], 11, v[132:133]
	v_exp_f32_e32 v112, v112
	v_mul_f32_e32 v134, 0xbfb8aa3b, v13
	v_exp_f32_e32 v136, v134
	v_lshl_add_u64 v[134:135], v[130:131], 0, v[132:133]
	v_mul_f32_e32 v131, 0xbfb8aa3b, v14
	v_exp_f32_e32 v132, v131
	v_mul_f32_e32 v131, 0xbfb8aa3b, v15
	v_exp_f32_e32 v133, v131
	v_add_f32_e32 v112, 1.0, v112
	v_rcp_f32_e32 v130, v112
	v_add_f32_e32 v112, 1.0, v136
	v_rcp_f32_e32 v131, v112
	v_add_f32_e32 v112, 1.0, v132
	v_rcp_f32_e32 v132, v112
	v_add_f32_e32 v112, 1.0, v133
	v_mul_f32_e32 v133, 0xbfb8aa3b, v4
	v_exp_f32_e32 v136, v133
	v_mul_f32_e32 v133, 0xbfb8aa3b, v5
	v_exp_f32_e32 v137, v133
	v_rcp_f32_e32 v133, v112
	v_add_f32_e32 v112, 1.0, v136
	v_rcp_f32_e32 v136, v112
	v_add_f32_e32 v112, 1.0, v137
	v_mul_f32_e32 v137, 0xbfb8aa3b, v6
	v_exp_f32_e32 v138, v137
	v_mul_f32_e32 v137, 0xbfb8aa3b, v7
	v_exp_f32_e32 v139, v137
	v_rcp_f32_e32 v137, v112
	v_add_f32_e32 v112, 1.0, v138
	v_rcp_f32_e32 v138, v112
	v_add_f32_e32 v112, 1.0, v139
	v_rcp_f32_e32 v139, v112
	v_pk_mul_f32 v[130:131], v[12:13], v[130:131]
	v_pk_mul_f32 v[132:133], v[14:15], v[132:133]
	v_pk_mul_f32 v[136:137], v[4:5], v[136:137]
	v_pk_mul_f32 v[138:139], v[6:7], v[138:139]
	v_mul_f32_e32 v112, 0xbfb8aa3b, v8
	v_cvt_pk_bf16_f32 v130, v130, v131
	v_cvt_pk_bf16_f32 v131, v132, v133
	v_cvt_pk_bf16_f32 v132, v136, v137
	v_cvt_pk_bf16_f32 v133, v138, v139
	v_lshl_add_u64 v[136:137], v[134:135], 0, s[4:5]
	v_exp_f32_e32 v112, v112
	v_mul_f32_e32 v138, 0xbfb8aa3b, v9
	v_exp_f32_e32 v138, v138
	global_store_dwordx4 v[136:137], v[130:133], off
	v_add_f32_e32 v112, 1.0, v112
	v_lshl_add_u64 v[134:135], v[134:135], 0, s[6:7]
	v_mul_f32_e32 v131, 0xbfb8aa3b, v10
	v_exp_f32_e32 v132, v131
	v_mul_f32_e32 v131, 0xbfb8aa3b, v11
	v_exp_f32_e32 v133, v131
	v_rcp_f32_e32 v130, v112
	v_add_f32_e32 v112, 1.0, v138
	v_rcp_f32_e32 v131, v112
	v_add_f32_e32 v112, 1.0, v132
	v_rcp_f32_e32 v132, v112
	v_add_f32_e32 v112, 1.0, v133
	v_mul_f32_e32 v133, 0xbfb8aa3b, v0
	v_exp_f32_e32 v136, v133
	v_mul_f32_e32 v133, 0xbfb8aa3b, v1
	v_exp_f32_e32 v137, v133
	v_rcp_f32_e32 v133, v112
	v_add_f32_e32 v112, 1.0, v136
	v_rcp_f32_e32 v136, v112
	v_add_f32_e32 v112, 1.0, v137
	v_mul_f32_e32 v137, 0xbfb8aa3b, v2
	v_exp_f32_e32 v138, v137
	v_mul_f32_e32 v137, 0xbfb8aa3b, v3
	v_exp_f32_e32 v139, v137
	v_rcp_f32_e32 v137, v112
	v_add_f32_e32 v112, 1.0, v138
	v_rcp_f32_e32 v138, v112
	v_add_f32_e32 v112, 1.0, v139
	v_rcp_f32_e32 v139, v112
	v_pk_mul_f32 v[130:131], v[8:9], v[130:131]
	v_pk_mul_f32 v[132:133], v[10:11], v[132:133]
	v_pk_mul_f32 v[136:137], v[0:1], v[136:137]
	v_pk_mul_f32 v[138:139], v[2:3], v[138:139]
	v_cvt_pk_bf16_f32 v130, v130, v131
	v_cvt_pk_bf16_f32 v131, v132, v133
	v_cvt_pk_bf16_f32 v132, v136, v137
	v_cvt_pk_bf16_f32 v133, v138, v139
	global_store_dwordx4 v[134:135], v[130:133], off
	s_branch .LBB0_974
.Lgate_wt:
	s_and_b64 s[4:5], s[22:23], exec
	s_mov_b64 s[4:5], s[0:1]
	s_cselect_b32 s6, -3, -6
	s_load_dwordx2 s[4:5], s[4:5], 0xd0
	s_add_i32 s6, s6, s74
	s_lshl_b32 s6, s6, 8
	s_ashr_i32 s7, s6, 31
	s_lshl_b64 s[6:7], s[6:7], 1
	s_waitcnt lgkmcnt(0)
	s_add_u32 s4, s4, s6
	v_lshlrev_b32_e32 v130, 3, v191
	s_addc_u32 s5, s5, s7
	v_ashrrev_i32_e32 v131, 31, v130
	v_readlane_b32 s6, v254, 45
	v_lshl_add_u64 v[130:131], v[130:131], 1, s[4:5]
	s_mov_b64 s[4:5], 0x6000000
	v_or_b32_e32 v112, s6, v189
	v_lshl_add_u64 v[130:131], v[130:131], 0, s[4:5]
	v_readlane_b32 s4, v254, 36
	s_cmp_eq_u32 s39, 3
	v_readlane_b32 s5, v254, 37
	v_lshl_add_u32 v132, s4, 8, v112
	v_ashrrev_i32_e32 v133, 31, v132
	v_mul_f32_e32 v112, 0xbfb8aa3b, v126
	v_lshlrev_b64 v[134:135], 11, v[132:133]
	v_exp_f32_e32 v112, v112
	v_mul_f32_e32 v133, 0xbfb8aa3b, v127
	v_exp_f32_e32 v133, v133
	v_lshl_add_u64 v[138:139], v[130:131], 0, v[134:135]
	v_add_f32_e32 v112, 1.0, v112
	v_rcp_f32_e32 v134, v112
	v_add_f32_e32 v112, 1.0, v133
	v_mul_f32_e32 v133, 0xbfb8aa3b, v128
	v_exp_f32_e32 v133, v133
	v_mul_f32_e32 v135, 0xbfb8aa3b, v129
	v_exp_f32_e32 v137, v135
	v_rcp_f32_e32 v135, v112
	v_add_f32_e32 v112, 1.0, v133
	v_mul_f32_e32 v133, 0xbfb8aa3b, v122
	v_rcp_f32_e32 v136, v112
	v_add_f32_e32 v112, 1.0, v137
	v_exp_f32_e32 v133, v133
	v_mul_f32_e32 v137, 0xbfb8aa3b, v123
	v_exp_f32_e32 v141, v137
	v_rcp_f32_e32 v137, v112
	v_add_f32_e32 v112, 1.0, v133
	v_mul_f32_e32 v133, 0xbfb8aa3b, v124
	v_rcp_f32_e32 v140, v112
	v_add_f32_e32 v112, 1.0, v141
	v_exp_f32_e32 v133, v133
	v_mul_f32_e32 v141, 0xbfb8aa3b, v125
	v_exp_f32_e32 v143, v141
	v_rcp_f32_e32 v141, v112
	v_add_f32_e32 v112, 1.0, v133
	v_rcp_f32_e32 v142, v112
	v_add_f32_e32 v112, 1.0, v143
	v_rcp_f32_e32 v143, v112
	v_mul_f32_e32 v112, 0xbfb8aa3b, v118
	v_exp_f32_e32 v112, v112
	v_mul_f32_e32 v133, 0xbfb8aa3b, v119
	v_readlane_b32 s4, v255, 29
	v_exp_f32_e32 v133, v133
	s_cselect_b32 s4, s19, s4
	v_readlane_b32 s5, v255, 28
	v_readlane_b32 s6, v255, 30
	v_pk_mul_f32 v[134:135], v[126:127], v[134:135]
	v_pk_mul_f32 v[136:137], v[128:129], v[136:137]
	v_pk_mul_f32 v[140:141], v[122:123], v[140:141]
	v_pk_mul_f32 v[142:143], v[124:125], v[142:143]
	s_cselect_b32 s6, s5, s6
	s_lshl_b32 s4, s4, 1
	s_mov_b32 s5, s15
	v_cvt_pk_bf16_f32 v134, v134, v135
	v_cvt_pk_bf16_f32 v135, v136, v137
	v_cvt_pk_bf16_f32 v136, v140, v141
	v_cvt_pk_bf16_f32 v137, v142, v143
	v_lshl_add_u64 v[140:141], v[138:139], 0, s[4:5]
	v_add_f32_e32 v112, 1.0, v112
	global_store_dwordx4 v[140:141], v[134:137], off sc1
	s_lshl_b32 s6, s6, 1
	s_mov_b32 s7, s15
	v_rcp_f32_e32 v134, v112
	v_add_f32_e32 v112, 1.0, v133
	v_mul_f32_e32 v133, 0xbfb8aa3b, v120
	v_exp_f32_e32 v133, v133
	v_mul_f32_e32 v135, 0xbfb8aa3b, v121
	v_exp_f32_e32 v137, v135
	v_rcp_f32_e32 v135, v112
	v_add_f32_e32 v112, 1.0, v133
	v_mul_f32_e32 v133, 0xbfb8aa3b, v114
	v_rcp_f32_e32 v136, v112
	v_add_f32_e32 v112, 1.0, v137
	v_exp_f32_e32 v133, v133
	v_mul_f32_e32 v137, 0xbfb8aa3b, v115
	v_exp_f32_e32 v141, v137
	v_rcp_f32_e32 v137, v112
	v_add_f32_e32 v112, 1.0, v133
	v_mul_f32_e32 v133, 0xbfb8aa3b, v116
	v_rcp_f32_e32 v140, v112
	v_add_f32_e32 v112, 1.0, v141
	v_exp_f32_e32 v133, v133
	v_mul_f32_e32 v141, 0xbfb8aa3b, v117
	v_exp_f32_e32 v143, v141
	v_rcp_f32_e32 v141, v112
	v_add_f32_e32 v112, 1.0, v133
	v_rcp_f32_e32 v142, v112
	v_add_f32_e32 v112, 1.0, v143
	v_rcp_f32_e32 v143, v112
	v_mul_f32_e32 v112, 0xbfb8aa3b, v108
	v_pk_mul_f32 v[134:135], v[118:119], v[134:135]
	v_pk_mul_f32 v[136:137], v[120:121], v[136:137]
	v_pk_mul_f32 v[140:141], v[114:115], v[140:141]
	v_pk_mul_f32 v[142:143], v[116:117], v[142:143]
	v_exp_f32_e32 v112, v112
	v_mul_f32_e32 v133, 0xbfb8aa3b, v109
	v_cvt_pk_bf16_f32 v134, v134, v135
	v_cvt_pk_bf16_f32 v135, v136, v137
	v_cvt_pk_bf16_f32 v136, v140, v141
	v_cvt_pk_bf16_f32 v137, v142, v143
	v_lshl_add_u64 v[138:139], v[138:139], 0, s[6:7]
	v_exp_f32_e32 v133, v133
	global_store_dwordx4 v[138:139], v[134:137], off sc1
	v_add_f32_e32 v112, 1.0, v112
	s_nop 0
	v_or_b32_e32 v134, 16, v132
	v_ashrrev_i32_e32 v135, 31, v134
	v_lshlrev_b64 v[134:135], 11, v[134:135]
	v_lshl_add_u64 v[138:139], v[130:131], 0, v[134:135]
	v_rcp_f32_e32 v134, v112
	v_add_f32_e32 v112, 1.0, v133
	v_mul_f32_e32 v133, 0xbfb8aa3b, v110
	v_exp_f32_e32 v133, v133
	v_mul_f32_e32 v135, 0xbfb8aa3b, v111
	v_exp_f32_e32 v137, v135
	v_rcp_f32_e32 v135, v112
	v_add_f32_e32 v112, 1.0, v133
	v_mul_f32_e32 v133, 0xbfb8aa3b, v104
	v_rcp_f32_e32 v136, v112
	v_add_f32_e32 v112, 1.0, v137
	v_exp_f32_e32 v133, v133
	v_mul_f32_e32 v137, 0xbfb8aa3b, v105
	v_exp_f32_e32 v141, v137
	v_rcp_f32_e32 v137, v112
	v_add_f32_e32 v112, 1.0, v133
	v_mul_f32_e32 v133, 0xbfb8aa3b, v106
	v_rcp_f32_e32 v140, v112
	v_add_f32_e32 v112, 1.0, v141
	v_exp_f32_e32 v133, v133
	v_mul_f32_e32 v141, 0xbfb8aa3b, v107
	v_exp_f32_e32 v143, v141
	v_rcp_f32_e32 v141, v112
	v_add_f32_e32 v112, 1.0, v133
	v_rcp_f32_e32 v142, v112
	v_add_f32_e32 v112, 1.0, v143
	v_rcp_f32_e32 v143, v112
	v_mul_f32_e32 v112, 0xbfb8aa3b, v100
	v_exp_f32_e32 v112, v112
	v_mul_f32_e32 v133, 0xbfb8aa3b, v101
	v_exp_f32_e32 v133, v133
	v_pk_mul_f32 v[134:135], v[108:109], v[134:135]
	v_pk_mul_f32 v[136:137], v[110:111], v[136:137]
	v_pk_mul_f32 v[140:141], v[104:105], v[140:141]
	v_pk_mul_f32 v[142:143], v[106:107], v[142:143]
	v_cvt_pk_bf16_f32 v134, v134, v135
	v_cvt_pk_bf16_f32 v135, v136, v137
	v_cvt_pk_bf16_f32 v136, v140, v141
	v_cvt_pk_bf16_f32 v137, v142, v143
	v_lshl_add_u64 v[140:141], v[138:139], 0, s[4:5]
	v_add_f32_e32 v112, 1.0, v112
	global_store_dwordx4 v[140:141], v[134:137], off sc1
	v_lshl_add_u64 v[138:139], v[138:139], 0, s[6:7]
	s_nop 0
	v_rcp_f32_e32 v134, v112
	v_add_f32_e32 v112, 1.0, v133
	v_mul_f32_e32 v133, 0xbfb8aa3b, v102
	v_exp_f32_e32 v133, v133
	v_mul_f32_e32 v135, 0xbfb8aa3b, v103
	v_exp_f32_e32 v137, v135
	v_rcp_f32_e32 v135, v112
	v_add_f32_e32 v112, 1.0, v133
	v_mul_f32_e32 v133, 0xbfb8aa3b, v96
	v_rcp_f32_e32 v136, v112
	v_add_f32_e32 v112, 1.0, v137
	v_exp_f32_e32 v133, v133
	v_mul_f32_e32 v137, 0xbfb8aa3b, v97
	v_exp_f32_e32 v141, v137
	v_rcp_f32_e32 v137, v112
	v_add_f32_e32 v112, 1.0, v133
	v_mul_f32_e32 v133, 0xbfb8aa3b, v98
	v_rcp_f32_e32 v140, v112
	v_add_f32_e32 v112, 1.0, v141
	v_exp_f32_e32 v133, v133
	v_mul_f32_e32 v141, 0xbfb8aa3b, v99
	v_exp_f32_e32 v143, v141
	v_rcp_f32_e32 v141, v112
	v_add_f32_e32 v112, 1.0, v133
	v_rcp_f32_e32 v142, v112
	v_add_f32_e32 v112, 1.0, v143
	v_rcp_f32_e32 v143, v112
	v_mul_f32_e32 v112, 0xbfb8aa3b, v92
	v_pk_mul_f32 v[134:135], v[100:101], v[134:135]
	v_pk_mul_f32 v[136:137], v[102:103], v[136:137]
	v_pk_mul_f32 v[140:141], v[96:97], v[140:141]
	v_pk_mul_f32 v[142:143], v[98:99], v[142:143]
	v_exp_f32_e32 v112, v112
	v_mul_f32_e32 v133, 0xbfb8aa3b, v93
	v_cvt_pk_bf16_f32 v134, v134, v135
	v_cvt_pk_bf16_f32 v135, v136, v137
	v_cvt_pk_bf16_f32 v136, v140, v141
	v_cvt_pk_bf16_f32 v137, v142, v143
	v_exp_f32_e32 v133, v133
	global_store_dwordx4 v[138:139], v[134:137], off sc1
	v_add_f32_e32 v112, 1.0, v112
	s_nop 0
	v_or_b32_e32 v134, 32, v132
	v_ashrrev_i32_e32 v135, 31, v134
	v_lshlrev_b64 v[134:135], 11, v[134:135]
	v_lshl_add_u64 v[138:139], v[130:131], 0, v[134:135]
	v_rcp_f32_e32 v134, v112
	v_add_f32_e32 v112, 1.0, v133
	v_mul_f32_e32 v133, 0xbfb8aa3b, v94
	v_exp_f32_e32 v133, v133
	v_mul_f32_e32 v135, 0xbfb8aa3b, v95
	v_exp_f32_e32 v137, v135
	v_rcp_f32_e32 v135, v112
	v_add_f32_e32 v112, 1.0, v133
	v_mul_f32_e32 v133, 0xbfb8aa3b, v88
	v_rcp_f32_e32 v136, v112
	v_add_f32_e32 v112, 1.0, v137
	v_exp_f32_e32 v133, v133
	v_mul_f32_e32 v137, 0xbfb8aa3b, v89
	v_exp_f32_e32 v141, v137
	v_rcp_f32_e32 v137, v112
	v_add_f32_e32 v112, 1.0, v133
	v_mul_f32_e32 v133, 0xbfb8aa3b, v90
	v_rcp_f32_e32 v140, v112
	v_add_f32_e32 v112, 1.0, v141
	v_exp_f32_e32 v133, v133
	v_mul_f32_e32 v141, 0xbfb8aa3b, v91
	v_exp_f32_e32 v143, v141
	v_rcp_f32_e32 v141, v112
	v_add_f32_e32 v112, 1.0, v133
	v_rcp_f32_e32 v142, v112
	v_add_f32_e32 v112, 1.0, v143
	v_rcp_f32_e32 v143, v112
	v_mul_f32_e32 v112, 0xbfb8aa3b, v84
	v_exp_f32_e32 v112, v112
	v_mul_f32_e32 v133, 0xbfb8aa3b, v85
	v_exp_f32_e32 v133, v133
	v_pk_mul_f32 v[134:135], v[92:93], v[134:135]
	v_pk_mul_f32 v[136:137], v[94:95], v[136:137]
	v_pk_mul_f32 v[140:141], v[88:89], v[140:141]
	v_pk_mul_f32 v[142:143], v[90:91], v[142:143]
	v_cvt_pk_bf16_f32 v134, v134, v135
	v_cvt_pk_bf16_f32 v135, v136, v137
	v_cvt_pk_bf16_f32 v136, v140, v141
	v_cvt_pk_bf16_f32 v137, v142, v143
	v_lshl_add_u64 v[140:141], v[138:139], 0, s[4:5]
	v_add_f32_e32 v112, 1.0, v112
	global_store_dwordx4 v[140:141], v[134:137], off sc1
	v_lshl_add_u64 v[138:139], v[138:139], 0, s[6:7]
	s_nop 0
	v_rcp_f32_e32 v134, v112
	v_add_f32_e32 v112, 1.0, v133
	v_mul_f32_e32 v133, 0xbfb8aa3b, v86
	v_exp_f32_e32 v133, v133
	v_mul_f32_e32 v135, 0xbfb8aa3b, v87
	v_exp_f32_e32 v137, v135
	v_rcp_f32_e32 v135, v112
	v_add_f32_e32 v112, 1.0, v133
	v_mul_f32_e32 v133, 0xbfb8aa3b, v80
	v_rcp_f32_e32 v136, v112
	v_add_f32_e32 v112, 1.0, v137
	v_exp_f32_e32 v133, v133
	v_mul_f32_e32 v137, 0xbfb8aa3b, v81
	v_exp_f32_e32 v141, v137
	v_rcp_f32_e32 v137, v112
	v_add_f32_e32 v112, 1.0, v133
	v_mul_f32_e32 v133, 0xbfb8aa3b, v82
	v_rcp_f32_e32 v140, v112
	v_add_f32_e32 v112, 1.0, v141
	v_exp_f32_e32 v133, v133
	v_mul_f32_e32 v141, 0xbfb8aa3b, v83
	v_exp_f32_e32 v143, v141
	v_rcp_f32_e32 v141, v112
	v_add_f32_e32 v112, 1.0, v133
	v_rcp_f32_e32 v142, v112
	v_add_f32_e32 v112, 1.0, v143
	v_rcp_f32_e32 v143, v112
	v_mul_f32_e32 v112, 0xbfb8aa3b, v76
	v_pk_mul_f32 v[134:135], v[84:85], v[134:135]
	v_pk_mul_f32 v[136:137], v[86:87], v[136:137]
	v_pk_mul_f32 v[140:141], v[80:81], v[140:141]
	v_pk_mul_f32 v[142:143], v[82:83], v[142:143]
	v_exp_f32_e32 v112, v112
	v_mul_f32_e32 v133, 0xbfb8aa3b, v77
	v_cvt_pk_bf16_f32 v134, v134, v135
	v_cvt_pk_bf16_f32 v135, v136, v137
	v_cvt_pk_bf16_f32 v136, v140, v141
	v_cvt_pk_bf16_f32 v137, v142, v143
	v_exp_f32_e32 v133, v133
	global_store_dwordx4 v[138:139], v[134:137], off sc1
	v_add_f32_e32 v112, 1.0, v112
	s_nop 0
	v_or_b32_e32 v134, 48, v132
	v_ashrrev_i32_e32 v135, 31, v134
	v_lshlrev_b64 v[134:135], 11, v[134:135]
	v_lshl_add_u64 v[138:139], v[130:131], 0, v[134:135]
	v_rcp_f32_e32 v134, v112
	v_add_f32_e32 v112, 1.0, v133
	v_mul_f32_e32 v133, 0xbfb8aa3b, v78
	v_exp_f32_e32 v133, v133
	v_mul_f32_e32 v135, 0xbfb8aa3b, v79
	v_exp_f32_e32 v137, v135
	v_rcp_f32_e32 v135, v112
	v_add_f32_e32 v112, 1.0, v133
	v_mul_f32_e32 v133, 0xbfb8aa3b, v72
	v_rcp_f32_e32 v136, v112
	v_add_f32_e32 v112, 1.0, v137
	v_exp_f32_e32 v133, v133
	v_mul_f32_e32 v137, 0xbfb8aa3b, v73
	v_exp_f32_e32 v141, v137
	v_rcp_f32_e32 v137, v112
	v_add_f32_e32 v112, 1.0, v133
	v_mul_f32_e32 v133, 0xbfb8aa3b, v74
	v_rcp_f32_e32 v140, v112
	v_add_f32_e32 v112, 1.0, v141
	v_exp_f32_e32 v133, v133
	v_mul_f32_e32 v141, 0xbfb8aa3b, v75
	v_exp_f32_e32 v143, v141
	v_rcp_f32_e32 v141, v112
	v_add_f32_e32 v112, 1.0, v133
	v_rcp_f32_e32 v142, v112
	v_add_f32_e32 v112, 1.0, v143
	v_rcp_f32_e32 v143, v112
	v_mul_f32_e32 v112, 0xbfb8aa3b, v68
	v_exp_f32_e32 v112, v112
	v_mul_f32_e32 v133, 0xbfb8aa3b, v69
	v_exp_f32_e32 v133, v133
	v_pk_mul_f32 v[134:135], v[76:77], v[134:135]
	v_pk_mul_f32 v[136:137], v[78:79], v[136:137]
	v_pk_mul_f32 v[140:141], v[72:73], v[140:141]
	v_pk_mul_f32 v[142:143], v[74:75], v[142:143]
	v_cvt_pk_bf16_f32 v134, v134, v135
	v_cvt_pk_bf16_f32 v135, v136, v137
	v_cvt_pk_bf16_f32 v136, v140, v141
	v_cvt_pk_bf16_f32 v137, v142, v143
	v_lshl_add_u64 v[140:141], v[138:139], 0, s[4:5]
	v_add_f32_e32 v112, 1.0, v112
	global_store_dwordx4 v[140:141], v[134:137], off sc1
	v_lshl_add_u64 v[138:139], v[138:139], 0, s[6:7]
	s_nop 0
	v_rcp_f32_e32 v134, v112
	v_add_f32_e32 v112, 1.0, v133
	v_mul_f32_e32 v133, 0xbfb8aa3b, v70
	v_exp_f32_e32 v133, v133
	v_mul_f32_e32 v135, 0xbfb8aa3b, v71
	v_exp_f32_e32 v137, v135
	v_rcp_f32_e32 v135, v112
	v_add_f32_e32 v112, 1.0, v133
	v_mul_f32_e32 v133, 0xbfb8aa3b, v64
	v_rcp_f32_e32 v136, v112
	v_add_f32_e32 v112, 1.0, v137
	v_exp_f32_e32 v133, v133
	v_mul_f32_e32 v137, 0xbfb8aa3b, v65
	v_exp_f32_e32 v141, v137
	v_rcp_f32_e32 v137, v112
	v_add_f32_e32 v112, 1.0, v133
	v_mul_f32_e32 v133, 0xbfb8aa3b, v66
	v_rcp_f32_e32 v140, v112
	v_add_f32_e32 v112, 1.0, v141
	v_exp_f32_e32 v133, v133
	v_mul_f32_e32 v141, 0xbfb8aa3b, v67
	v_exp_f32_e32 v143, v141
	v_rcp_f32_e32 v141, v112
	v_add_f32_e32 v112, 1.0, v133
	v_rcp_f32_e32 v142, v112
	v_add_f32_e32 v112, 1.0, v143
	v_rcp_f32_e32 v143, v112
	v_mul_f32_e32 v112, 0xbfb8aa3b, v60
	v_pk_mul_f32 v[134:135], v[68:69], v[134:135]
	v_pk_mul_f32 v[136:137], v[70:71], v[136:137]
	v_pk_mul_f32 v[140:141], v[64:65], v[140:141]
	v_pk_mul_f32 v[142:143], v[66:67], v[142:143]
	v_exp_f32_e32 v112, v112
	v_mul_f32_e32 v133, 0xbfb8aa3b, v61
	v_cvt_pk_bf16_f32 v134, v134, v135
	v_cvt_pk_bf16_f32 v135, v136, v137
	v_cvt_pk_bf16_f32 v136, v140, v141
	v_cvt_pk_bf16_f32 v137, v142, v143
	v_exp_f32_e32 v133, v133
	global_store_dwordx4 v[138:139], v[134:137], off sc1
	v_add_f32_e32 v112, 1.0, v112
	s_nop 0
	v_add_u32_e32 v134, 0x80, v132
	v_ashrrev_i32_e32 v135, 31, v134
	v_lshlrev_b64 v[134:135], 11, v[134:135]
	v_lshl_add_u64 v[138:139], v[130:131], 0, v[134:135]
	v_rcp_f32_e32 v134, v112
	v_add_f32_e32 v112, 1.0, v133
	v_mul_f32_e32 v133, 0xbfb8aa3b, v62
	v_exp_f32_e32 v133, v133
	v_mul_f32_e32 v135, 0xbfb8aa3b, v63
	v_exp_f32_e32 v137, v135
	v_rcp_f32_e32 v135, v112
	v_add_f32_e32 v112, 1.0, v133
	v_mul_f32_e32 v133, 0xbfb8aa3b, v56
	v_rcp_f32_e32 v136, v112
	v_add_f32_e32 v112, 1.0, v137
	v_exp_f32_e32 v133, v133
	v_mul_f32_e32 v137, 0xbfb8aa3b, v57
	v_exp_f32_e32 v141, v137
	v_rcp_f32_e32 v137, v112
	v_add_f32_e32 v112, 1.0, v133
	v_mul_f32_e32 v133, 0xbfb8aa3b, v58
	v_rcp_f32_e32 v140, v112
	v_add_f32_e32 v112, 1.0, v141
	v_exp_f32_e32 v133, v133
	v_mul_f32_e32 v141, 0xbfb8aa3b, v59
	v_exp_f32_e32 v143, v141
	v_rcp_f32_e32 v141, v112
	v_add_f32_e32 v112, 1.0, v133
	v_rcp_f32_e32 v142, v112
	v_add_f32_e32 v112, 1.0, v143
	v_rcp_f32_e32 v143, v112
	v_mul_f32_e32 v112, 0xbfb8aa3b, v52
	v_exp_f32_e32 v112, v112
	v_mul_f32_e32 v133, 0xbfb8aa3b, v53
	v_exp_f32_e32 v133, v133
	v_pk_mul_f32 v[134:135], v[60:61], v[134:135]
	v_pk_mul_f32 v[136:137], v[62:63], v[136:137]
	v_pk_mul_f32 v[140:141], v[56:57], v[140:141]
	v_pk_mul_f32 v[142:143], v[58:59], v[142:143]
	v_cvt_pk_bf16_f32 v134, v134, v135
	v_cvt_pk_bf16_f32 v135, v136, v137
	v_cvt_pk_bf16_f32 v136, v140, v141
	v_cvt_pk_bf16_f32 v137, v142, v143
	v_lshl_add_u64 v[140:141], v[138:139], 0, s[4:5]
	v_add_f32_e32 v112, 1.0, v112
	global_store_dwordx4 v[140:141], v[134:137], off sc1
	v_lshl_add_u64 v[138:139], v[138:139], 0, s[6:7]
	s_nop 0
	v_rcp_f32_e32 v134, v112
	v_add_f32_e32 v112, 1.0, v133
	v_mul_f32_e32 v133, 0xbfb8aa3b, v54
	v_exp_f32_e32 v133, v133
	v_mul_f32_e32 v135, 0xbfb8aa3b, v55
	v_exp_f32_e32 v137, v135
	v_rcp_f32_e32 v135, v112
	v_add_f32_e32 v112, 1.0, v133
	v_mul_f32_e32 v133, 0xbfb8aa3b, v48
	v_rcp_f32_e32 v136, v112
	v_add_f32_e32 v112, 1.0, v137
	v_exp_f32_e32 v133, v133
	v_mul_f32_e32 v137, 0xbfb8aa3b, v49
	v_exp_f32_e32 v141, v137
	v_rcp_f32_e32 v137, v112
	v_add_f32_e32 v112, 1.0, v133
	v_mul_f32_e32 v133, 0xbfb8aa3b, v50
	v_rcp_f32_e32 v140, v112
	v_add_f32_e32 v112, 1.0, v141
	v_exp_f32_e32 v133, v133
	v_mul_f32_e32 v141, 0xbfb8aa3b, v51
	v_exp_f32_e32 v143, v141
	v_rcp_f32_e32 v141, v112
	v_add_f32_e32 v112, 1.0, v133
	v_rcp_f32_e32 v142, v112
	v_add_f32_e32 v112, 1.0, v143
	v_rcp_f32_e32 v143, v112
	v_mul_f32_e32 v112, 0xbfb8aa3b, v44
	v_pk_mul_f32 v[134:135], v[52:53], v[134:135]
	v_pk_mul_f32 v[136:137], v[54:55], v[136:137]
	v_pk_mul_f32 v[140:141], v[48:49], v[140:141]
	v_pk_mul_f32 v[142:143], v[50:51], v[142:143]
	v_exp_f32_e32 v112, v112
	v_mul_f32_e32 v133, 0xbfb8aa3b, v45
	v_cvt_pk_bf16_f32 v134, v134, v135
	v_cvt_pk_bf16_f32 v135, v136, v137
	v_cvt_pk_bf16_f32 v136, v140, v141
	v_cvt_pk_bf16_f32 v137, v142, v143
	v_exp_f32_e32 v133, v133
	global_store_dwordx4 v[138:139], v[134:137], off sc1
	v_add_f32_e32 v112, 1.0, v112
	s_nop 0
	v_add_u32_e32 v134, 0x90, v132
	v_ashrrev_i32_e32 v135, 31, v134
	v_lshlrev_b64 v[134:135], 11, v[134:135]
	v_lshl_add_u64 v[138:139], v[130:131], 0, v[134:135]
	v_rcp_f32_e32 v134, v112
	v_add_f32_e32 v112, 1.0, v133
	v_mul_f32_e32 v133, 0xbfb8aa3b, v46
	v_exp_f32_e32 v133, v133
	v_mul_f32_e32 v135, 0xbfb8aa3b, v47
	v_exp_f32_e32 v137, v135
	v_rcp_f32_e32 v135, v112
	v_add_f32_e32 v112, 1.0, v133
	v_mul_f32_e32 v133, 0xbfb8aa3b, v40
	v_rcp_f32_e32 v136, v112
	v_add_f32_e32 v112, 1.0, v137
	v_exp_f32_e32 v133, v133
	v_mul_f32_e32 v137, 0xbfb8aa3b, v41
	v_exp_f32_e32 v141, v137
	v_rcp_f32_e32 v137, v112
	v_add_f32_e32 v112, 1.0, v133
	v_mul_f32_e32 v133, 0xbfb8aa3b, v42
	v_rcp_f32_e32 v140, v112
	v_add_f32_e32 v112, 1.0, v141
	v_exp_f32_e32 v133, v133
	v_mul_f32_e32 v141, 0xbfb8aa3b, v43
	v_exp_f32_e32 v143, v141
	v_rcp_f32_e32 v141, v112
	v_add_f32_e32 v112, 1.0, v133
	v_rcp_f32_e32 v142, v112
	v_add_f32_e32 v112, 1.0, v143
	v_rcp_f32_e32 v143, v112
	v_mul_f32_e32 v112, 0xbfb8aa3b, v36
	v_exp_f32_e32 v112, v112
	v_mul_f32_e32 v133, 0xbfb8aa3b, v37
	v_exp_f32_e32 v133, v133
	v_pk_mul_f32 v[134:135], v[44:45], v[134:135]
	v_pk_mul_f32 v[136:137], v[46:47], v[136:137]
	v_pk_mul_f32 v[140:141], v[40:41], v[140:141]
	v_pk_mul_f32 v[142:143], v[42:43], v[142:143]
	v_cvt_pk_bf16_f32 v134, v134, v135
	v_cvt_pk_bf16_f32 v135, v136, v137
	v_cvt_pk_bf16_f32 v136, v140, v141
	v_cvt_pk_bf16_f32 v137, v142, v143
	v_lshl_add_u64 v[140:141], v[138:139], 0, s[4:5]
	v_add_f32_e32 v112, 1.0, v112
	global_store_dwordx4 v[140:141], v[134:137], off sc1
	v_lshl_add_u64 v[138:139], v[138:139], 0, s[6:7]
	s_nop 0
	v_rcp_f32_e32 v134, v112
	v_add_f32_e32 v112, 1.0, v133
	v_mul_f32_e32 v133, 0xbfb8aa3b, v38
	v_exp_f32_e32 v133, v133
	v_mul_f32_e32 v135, 0xbfb8aa3b, v39
	v_exp_f32_e32 v137, v135
	v_rcp_f32_e32 v135, v112
	v_add_f32_e32 v112, 1.0, v133
	v_mul_f32_e32 v133, 0xbfb8aa3b, v32
	v_rcp_f32_e32 v136, v112
	v_add_f32_e32 v112, 1.0, v137
	v_exp_f32_e32 v133, v133
	v_mul_f32_e32 v137, 0xbfb8aa3b, v33
	v_exp_f32_e32 v141, v137
	v_rcp_f32_e32 v137, v112
	v_add_f32_e32 v112, 1.0, v133
	v_mul_f32_e32 v133, 0xbfb8aa3b, v34
	v_rcp_f32_e32 v140, v112
	v_add_f32_e32 v112, 1.0, v141
	v_exp_f32_e32 v133, v133
	v_mul_f32_e32 v141, 0xbfb8aa3b, v35
	v_exp_f32_e32 v143, v141
	v_rcp_f32_e32 v141, v112
	v_add_f32_e32 v112, 1.0, v133
	v_rcp_f32_e32 v142, v112
	v_add_f32_e32 v112, 1.0, v143
	v_rcp_f32_e32 v143, v112
	v_mul_f32_e32 v112, 0xbfb8aa3b, v28
	v_pk_mul_f32 v[134:135], v[36:37], v[134:135]
	v_pk_mul_f32 v[136:137], v[38:39], v[136:137]
	v_pk_mul_f32 v[140:141], v[32:33], v[140:141]
	v_pk_mul_f32 v[142:143], v[34:35], v[142:143]
	v_exp_f32_e32 v112, v112
	v_mul_f32_e32 v133, 0xbfb8aa3b, v29
	v_cvt_pk_bf16_f32 v134, v134, v135
	v_cvt_pk_bf16_f32 v135, v136, v137
	v_cvt_pk_bf16_f32 v136, v140, v141
	v_cvt_pk_bf16_f32 v137, v142, v143
	v_exp_f32_e32 v133, v133
	global_store_dwordx4 v[138:139], v[134:137], off sc1
	v_add_f32_e32 v112, 1.0, v112
	s_nop 0
	v_add_u32_e32 v134, 0xa0, v132
	v_ashrrev_i32_e32 v135, 31, v134
	v_lshlrev_b64 v[134:135], 11, v[134:135]
	v_lshl_add_u64 v[138:139], v[130:131], 0, v[134:135]
	v_rcp_f32_e32 v134, v112
	v_add_f32_e32 v112, 1.0, v133
	v_mul_f32_e32 v133, 0xbfb8aa3b, v30
	v_exp_f32_e32 v133, v133
	v_mul_f32_e32 v135, 0xbfb8aa3b, v31
	v_exp_f32_e32 v137, v135
	v_rcp_f32_e32 v135, v112
	v_add_f32_e32 v112, 1.0, v133
	v_mul_f32_e32 v133, 0xbfb8aa3b, v24
	v_rcp_f32_e32 v136, v112
	v_add_f32_e32 v112, 1.0, v137
	v_exp_f32_e32 v133, v133
	v_mul_f32_e32 v137, 0xbfb8aa3b, v25
	v_exp_f32_e32 v141, v137
	v_rcp_f32_e32 v137, v112
	v_add_f32_e32 v112, 1.0, v133
	v_mul_f32_e32 v133, 0xbfb8aa3b, v26
	v_rcp_f32_e32 v140, v112
	v_add_f32_e32 v112, 1.0, v141
	v_exp_f32_e32 v133, v133
	v_mul_f32_e32 v141, 0xbfb8aa3b, v27
	v_exp_f32_e32 v143, v141
	v_rcp_f32_e32 v141, v112
	v_add_f32_e32 v112, 1.0, v133
	v_rcp_f32_e32 v142, v112
	v_add_f32_e32 v112, 1.0, v143
	v_rcp_f32_e32 v143, v112
	v_mul_f32_e32 v112, 0xbfb8aa3b, v20
	v_exp_f32_e32 v112, v112
	v_mul_f32_e32 v133, 0xbfb8aa3b, v21
	v_exp_f32_e32 v133, v133
	v_pk_mul_f32 v[134:135], v[28:29], v[134:135]
	v_pk_mul_f32 v[136:137], v[30:31], v[136:137]
	v_pk_mul_f32 v[140:141], v[24:25], v[140:141]
	v_pk_mul_f32 v[142:143], v[26:27], v[142:143]
	v_cvt_pk_bf16_f32 v134, v134, v135
	v_cvt_pk_bf16_f32 v135, v136, v137
	v_cvt_pk_bf16_f32 v136, v140, v141
	v_cvt_pk_bf16_f32 v137, v142, v143
	v_lshl_add_u64 v[140:141], v[138:139], 0, s[4:5]
	v_add_f32_e32 v112, 1.0, v112
	global_store_dwordx4 v[140:141], v[134:137], off sc1
	v_add_u32_e32 v132, 0xb0, v132
	v_lshl_add_u64 v[138:139], v[138:139], 0, s[6:7]
	v_rcp_f32_e32 v134, v112
	v_add_f32_e32 v112, 1.0, v133
	v_mul_f32_e32 v133, 0xbfb8aa3b, v22
	v_exp_f32_e32 v133, v133
	v_mul_f32_e32 v135, 0xbfb8aa3b, v23
	v_exp_f32_e32 v137, v135
	v_rcp_f32_e32 v135, v112
	v_add_f32_e32 v112, 1.0, v133
	v_mul_f32_e32 v133, 0xbfb8aa3b, v16
	v_rcp_f32_e32 v136, v112
	v_add_f32_e32 v112, 1.0, v137
	v_exp_f32_e32 v133, v133
	v_mul_f32_e32 v137, 0xbfb8aa3b, v17
	v_exp_f32_e32 v141, v137
	v_rcp_f32_e32 v137, v112
	v_add_f32_e32 v112, 1.0, v133
	v_mul_f32_e32 v133, 0xbfb8aa3b, v18
	v_rcp_f32_e32 v140, v112
	v_add_f32_e32 v112, 1.0, v141
	v_exp_f32_e32 v133, v133
	v_mul_f32_e32 v141, 0xbfb8aa3b, v19
	v_exp_f32_e32 v143, v141
	v_rcp_f32_e32 v141, v112
	v_add_f32_e32 v112, 1.0, v133
	v_rcp_f32_e32 v142, v112
	v_add_f32_e32 v112, 1.0, v143
	v_rcp_f32_e32 v143, v112
	v_pk_mul_f32 v[134:135], v[20:21], v[134:135]
	v_pk_mul_f32 v[136:137], v[22:23], v[136:137]
	v_pk_mul_f32 v[140:141], v[16:17], v[140:141]
	v_pk_mul_f32 v[142:143], v[18:19], v[142:143]
	v_cvt_pk_bf16_f32 v134, v134, v135
	v_cvt_pk_bf16_f32 v135, v136, v137
	v_cvt_pk_bf16_f32 v136, v140, v141
	v_cvt_pk_bf16_f32 v137, v142, v143
	v_ashrrev_i32_e32 v133, 31, v132
	v_mul_f32_e32 v112, 0xbfb8aa3b, v12
	global_store_dwordx4 v[138:139], v[134:137], off sc1
	v_lshlrev_b64 v[132:133], 11, v[132:133]
	v_exp_f32_e32 v112, v112
	v_mul_f32_e32 v134, 0xbfb8aa3b, v13
	v_exp_f32_e32 v136, v134
	v_lshl_add_u64 v[134:135], v[130:131], 0, v[132:133]
	v_mul_f32_e32 v131, 0xbfb8aa3b, v14
	v_exp_f32_e32 v132, v131
	v_mul_f32_e32 v131, 0xbfb8aa3b, v15
	v_exp_f32_e32 v133, v131
	v_add_f32_e32 v112, 1.0, v112
	v_rcp_f32_e32 v130, v112
	v_add_f32_e32 v112, 1.0, v136
	v_rcp_f32_e32 v131, v112
	v_add_f32_e32 v112, 1.0, v132
	v_rcp_f32_e32 v132, v112
	v_add_f32_e32 v112, 1.0, v133
	v_mul_f32_e32 v133, 0xbfb8aa3b, v4
	v_exp_f32_e32 v136, v133
	v_mul_f32_e32 v133, 0xbfb8aa3b, v5
	v_exp_f32_e32 v137, v133
	v_rcp_f32_e32 v133, v112
	v_add_f32_e32 v112, 1.0, v136
	v_rcp_f32_e32 v136, v112
	v_add_f32_e32 v112, 1.0, v137
	v_mul_f32_e32 v137, 0xbfb8aa3b, v6
	v_exp_f32_e32 v138, v137
	v_mul_f32_e32 v137, 0xbfb8aa3b, v7
	v_exp_f32_e32 v139, v137
	v_rcp_f32_e32 v137, v112
	v_add_f32_e32 v112, 1.0, v138
	v_rcp_f32_e32 v138, v112
	v_add_f32_e32 v112, 1.0, v139
	v_rcp_f32_e32 v139, v112
	v_pk_mul_f32 v[130:131], v[12:13], v[130:131]
	v_pk_mul_f32 v[132:133], v[14:15], v[132:133]
	v_pk_mul_f32 v[136:137], v[4:5], v[136:137]
	v_pk_mul_f32 v[138:139], v[6:7], v[138:139]
	v_mul_f32_e32 v112, 0xbfb8aa3b, v8
	v_cvt_pk_bf16_f32 v130, v130, v131
	v_cvt_pk_bf16_f32 v131, v132, v133
	v_cvt_pk_bf16_f32 v132, v136, v137
	v_cvt_pk_bf16_f32 v133, v138, v139
	v_lshl_add_u64 v[136:137], v[134:135], 0, s[4:5]
	v_exp_f32_e32 v112, v112
	v_mul_f32_e32 v138, 0xbfb8aa3b, v9
	v_exp_f32_e32 v138, v138
	global_store_dwordx4 v[136:137], v[130:133], off sc1
	v_add_f32_e32 v112, 1.0, v112
	v_lshl_add_u64 v[134:135], v[134:135], 0, s[6:7]
	v_mul_f32_e32 v131, 0xbfb8aa3b, v10
	v_exp_f32_e32 v132, v131
	v_mul_f32_e32 v131, 0xbfb8aa3b, v11
	v_exp_f32_e32 v133, v131
	v_rcp_f32_e32 v130, v112
	v_add_f32_e32 v112, 1.0, v138
	v_rcp_f32_e32 v131, v112
	v_add_f32_e32 v112, 1.0, v132
	v_rcp_f32_e32 v132, v112
	v_add_f32_e32 v112, 1.0, v133
	v_mul_f32_e32 v133, 0xbfb8aa3b, v0
	v_exp_f32_e32 v136, v133
	v_mul_f32_e32 v133, 0xbfb8aa3b, v1
	v_exp_f32_e32 v137, v133
	v_rcp_f32_e32 v133, v112
	v_add_f32_e32 v112, 1.0, v136
	v_rcp_f32_e32 v136, v112
	v_add_f32_e32 v112, 1.0, v137
	v_mul_f32_e32 v137, 0xbfb8aa3b, v2
	v_exp_f32_e32 v138, v137
	v_mul_f32_e32 v137, 0xbfb8aa3b, v3
	v_exp_f32_e32 v139, v137
	v_rcp_f32_e32 v137, v112
	v_add_f32_e32 v112, 1.0, v138
	v_rcp_f32_e32 v138, v112
	v_add_f32_e32 v112, 1.0, v139
	v_rcp_f32_e32 v139, v112
	v_pk_mul_f32 v[130:131], v[8:9], v[130:131]
	v_pk_mul_f32 v[132:133], v[10:11], v[132:133]
	v_pk_mul_f32 v[136:137], v[0:1], v[136:137]
	v_pk_mul_f32 v[138:139], v[2:3], v[138:139]
	v_cvt_pk_bf16_f32 v130, v130, v131
	v_cvt_pk_bf16_f32 v131, v132, v133
	v_cvt_pk_bf16_f32 v132, v136, v137
	v_cvt_pk_bf16_f32 v133, v138, v139
	global_store_dwordx4 v[134:135], v[130:133], off sc1
